# attention item epilogue: the 8 norm-weight loads hoisted ahead of the stores (one issue burst, counted vmcnt) instead of load-wait-store ladder
# baseline (speedup 1.0000x reference)
.LBB0_621:
	s_or_b64 exec, exec, s[8:9]
	ds_bpermute_b32 v4, v149, v113
	ds_bpermute_b32 v5, v149, v112
	v_readlane_b32 s80, v255, 22
	v_lshlrev_b32_e32 v3, 2, v3
	v_readlane_b32 s82, v255, 24
	s_waitcnt lgkmcnt(1)
	v_add_f32_e32 v4, v113, v4
	ds_bpermute_b32 v6, v148, v4
	s_waitcnt lgkmcnt(1)
	v_add_f32_e32 v5, v112, v5
	ds_bpermute_b32 v7, v148, v5
	v_readlane_b32 s83, v255, 25
	v_mov_b32_e32 v115, v2
	s_waitcnt lgkmcnt(1)
	v_add_f32_e32 v4, v4, v6
	v_div_scale_f32 v6, s[6:7], v4, v4, 1.0
	v_rcp_f32_e32 v8, v6
	s_waitcnt lgkmcnt(0)
	v_add_f32_e32 v5, v5, v7
	v_div_scale_f32 v7, vcc, 1.0, v4, 1.0
	v_fma_f32 v11, -v6, v8, 1.0
	v_fmac_f32_e32 v8, v11, v8
	v_div_scale_f32 v9, s[6:7], v5, v5, v150
	v_mul_f32_e32 v11, v7, v8
	v_rcp_f32_e32 v10, v9
	v_fma_f32 v12, -v6, v11, v7
	v_fmac_f32_e32 v11, v12, v8
	v_fma_f32 v6, -v6, v11, v7
	v_div_fmas_f32 v6, v6, v8, v11
	v_div_fixup_f32 v12, v6, v4, 1.0
	v_fma_f32 v4, -v9, v10, 1.0
	v_fmac_f32_e32 v10, v4, v10
	v_div_scale_f32 v4, vcc, v150, v5, v150
	v_mul_f32_e32 v6, v4, v10
	v_fma_f32 v7, -v9, v6, v4
	v_fmac_f32_e32 v6, v7, v10
	v_fma_f32 v4, -v9, v6, v4
	v_div_fmas_f32 v4, v4, v10, v6
	v_div_fixup_f32 v14, v4, v5, v150
	v_pk_mul_f32 v[8:9], v[80:81], v[14:15] op_sel_hi:[1,0]
	v_pk_mul_f32 v[40:41], v[82:83], v[14:15] op_sel_hi:[1,0]
	v_pk_fma_f32 v[36:37], v[96:97], v[12:13], v[8:9] op_sel_hi:[1,0,1] neg_lo:[0,0,1] neg_hi:[0,0,1]
	global_load_dwordx4 v[8:11], v3, s[82:83]
	global_load_dwordx4 v[160:163], v3, s[82:83] offset:64
	global_load_dwordx4 v[164:167], v3, s[82:83] offset:128
	global_load_dwordx4 v[168:171], v3, s[82:83] offset:192
	global_load_dwordx4 v[172:175], v3, s[82:83] offset:256
	global_load_dwordx4 v[176:179], v3, s[82:83] offset:320
	global_load_dwordx4 v[180:183], v3, s[82:83] offset:384
	global_load_dwordx4 v[184:187], v3, s[82:83] offset:448
	v_pk_mul_f32 v[4:5], v[88:89], v[14:15] op_sel_hi:[1,0]
	v_pk_mul_f32 v[6:7], v[90:91], v[14:15] op_sel_hi:[1,0]
	v_pk_mul_f32 v[38:39], v[36:37], v[36:37]
	v_pk_fma_f32 v[40:41], v[98:99], v[12:13], v[40:41] op_sel_hi:[1,0,1] neg_lo:[0,0,1] neg_hi:[0,0,1]
	v_pk_mul_f32 v[48:49], v[68:69], v[14:15] op_sel_hi:[1,0]
	v_pk_mul_f32 v[52:53], v[70:71], v[14:15] op_sel_hi:[1,0]
	v_pk_mul_f32 v[56:57], v[56:57], v[14:15] op_sel_hi:[1,0]
	v_pk_mul_f32 v[58:59], v[58:59], v[14:15] op_sel_hi:[1,0]
	v_pk_mul_f32 v[24:25], v[24:25], v[14:15] op_sel_hi:[1,0]
	v_pk_mul_f32 v[26:27], v[26:27], v[14:15] op_sel_hi:[1,0]
	v_pk_mul_f32 v[64:65], v[64:65], v[14:15] op_sel_hi:[1,0]
	v_pk_mul_f32 v[66:67], v[66:67], v[14:15] op_sel_hi:[1,0]
	v_pk_mul_f32 v[44:45], v[44:45], v[14:15] op_sel_hi:[1,0]
	v_pk_mul_f32 v[46:47], v[46:47], v[14:15] op_sel_hi:[1,0]
	v_pk_mul_f32 v[32:33], v[32:33], v[14:15] op_sel_hi:[1,0]
	v_pk_mul_f32 v[14:15], v[34:35], v[14:15] op_sel_hi:[1,0]
	v_pk_fma_f32 v[4:5], v[84:85], v[12:13], v[4:5] op_sel_hi:[1,0,1] neg_lo:[0,0,1] neg_hi:[0,0,1]
	v_pk_fma_f32 v[6:7], v[86:87], v[12:13], v[6:7] op_sel_hi:[1,0,1] neg_lo:[0,0,1] neg_hi:[0,0,1]
	v_pk_mul_f32 v[42:43], v[40:41], v[40:41]
	v_pk_fma_f32 v[48:49], v[92:93], v[12:13], v[48:49] op_sel_hi:[1,0,1] neg_lo:[0,0,1] neg_hi:[0,0,1]
	v_pk_fma_f32 v[52:53], v[94:95], v[12:13], v[52:53] op_sel_hi:[1,0,1] neg_lo:[0,0,1] neg_hi:[0,0,1]
	v_pk_fma_f32 v[56:57], v[76:77], v[12:13], v[56:57] op_sel_hi:[1,0,1] neg_lo:[0,0,1] neg_hi:[0,0,1]
	v_pk_fma_f32 v[58:59], v[78:79], v[12:13], v[58:59] op_sel_hi:[1,0,1] neg_lo:[0,0,1] neg_hi:[0,0,1]
	v_pk_fma_f32 v[24:25], v[72:73], v[12:13], v[24:25] op_sel_hi:[1,0,1] neg_lo:[0,0,1] neg_hi:[0,0,1]
	v_pk_fma_f32 v[26:27], v[74:75], v[12:13], v[26:27] op_sel_hi:[1,0,1] neg_lo:[0,0,1] neg_hi:[0,0,1]
	v_pk_fma_f32 v[60:61], v[60:61], v[12:13], v[64:65] op_sel_hi:[1,0,1] neg_lo:[0,0,1] neg_hi:[0,0,1]
	v_pk_fma_f32 v[62:63], v[62:63], v[12:13], v[66:67] op_sel_hi:[1,0,1] neg_lo:[0,0,1] neg_hi:[0,0,1]
	v_pk_fma_f32 v[28:29], v[28:29], v[12:13], v[44:45] op_sel_hi:[1,0,1] neg_lo:[0,0,1] neg_hi:[0,0,1]
	v_pk_fma_f32 v[30:31], v[30:31], v[12:13], v[46:47] op_sel_hi:[1,0,1] neg_lo:[0,0,1] neg_hi:[0,0,1]
	v_pk_fma_f32 v[20:21], v[20:21], v[12:13], v[32:33] op_sel_hi:[1,0,1] neg_lo:[0,0,1] neg_hi:[0,0,1]
	v_pk_fma_f32 v[12:13], v[22:23], v[12:13], v[14:15] op_sel_hi:[1,0,1] neg_lo:[0,0,1] neg_hi:[0,0,1]
	v_add_f32_e32 v22, v38, v39
	v_add_f32_e32 v22, v42, v22
	v_pk_mul_f32 v[50:51], v[48:49], v[48:49]
	v_add_f32_e32 v22, v43, v22
	v_add_f32_e32 v22, v50, v22
	v_pk_mul_f32 v[54:55], v[52:53], v[52:53]
	v_add_f32_e32 v22, v51, v22
	v_add_f32_e32 v22, v54, v22
	v_pk_mul_f32 v[68:69], v[56:57], v[56:57]
	v_add_f32_e32 v22, v55, v22
	v_add_f32_e32 v22, v68, v22
	v_pk_mul_f32 v[70:71], v[58:59], v[58:59]
	v_add_f32_e32 v22, v69, v22
	v_add_f32_e32 v22, v70, v22
	v_pk_mul_f32 v[72:73], v[24:25], v[24:25]
	v_add_f32_e32 v22, v71, v22
	v_add_f32_e32 v22, v72, v22
	v_pk_mul_f32 v[74:75], v[26:27], v[26:27]
	v_add_f32_e32 v22, v73, v22
	v_add_f32_e32 v22, v74, v22
	v_pk_mul_f32 v[64:65], v[60:61], v[60:61]
	v_add_f32_e32 v22, v75, v22
	v_add_f32_e32 v22, v64, v22
	v_pk_mul_f32 v[66:67], v[62:63], v[62:63]
	v_add_f32_e32 v22, v65, v22
	v_add_f32_e32 v22, v66, v22
	v_pk_mul_f32 v[44:45], v[28:29], v[28:29]
	v_add_f32_e32 v22, v67, v22
	v_add_f32_e32 v22, v44, v22
	v_pk_mul_f32 v[46:47], v[30:31], v[30:31]
	v_add_f32_e32 v22, v45, v22
	v_add_f32_e32 v22, v46, v22
	v_pk_mul_f32 v[32:33], v[20:21], v[20:21]
	v_add_f32_e32 v22, v47, v22
	v_add_f32_e32 v22, v32, v22
	v_pk_mul_f32 v[14:15], v[12:13], v[12:13]
	v_add_f32_e32 v22, v33, v22
	v_add_f32_e32 v14, v14, v22
	v_pk_mul_f32 v[16:17], v[4:5], v[4:5]
	v_add_f32_e32 v14, v15, v14
	v_add_f32_e32 v14, v16, v14
	v_pk_mul_f32 v[18:19], v[6:7], v[6:7]
	v_add_f32_e32 v14, v17, v14
	v_add_f32_e32 v14, v18, v14
	v_add_f32_e32 v14, v19, v14
	ds_bpermute_b32 v15, v149, v14
	s_mov_b32 s6, 0x800000
	v_readlane_b32 s81, v255, 23
	v_readlane_b32 s84, v255, 26
	v_readlane_b32 s85, v255, 27
	s_waitcnt lgkmcnt(0)
	v_add_f32_e32 v16, v14, v15
	ds_bpermute_b32 v17, v148, v16
	v_lshlrev_b64 v[14:15], 12, v[100:101]
	v_lshl_add_u64 v[14:15], s[44:45], 0, v[14:15]
	v_lshl_add_u64 v[0:1], v[0:1], 1, v[14:15]
	v_lshl_add_u64 v[0:1], v[0:1], 0, v[114:115]
	s_waitcnt lgkmcnt(0)
	v_add_f32_e32 v16, v16, v17
	v_fmamk_f32 v16, v16, 0x3c000000, v137
	v_mul_f32_e32 v17, 0x4b800000, v16
	v_cmp_gt_f32_e32 vcc, s6, v16
	v_readlane_b32 s86, v255, 28
	v_readlane_b32 s87, v255, 29
	v_cndmask_b32_e32 v16, v16, v17, vcc
	v_rsq_f32_e32 v16, v16
	v_readlane_b32 s88, v255, 30
	v_readlane_b32 s89, v255, 31
	v_readlane_b32 s90, v255, 32
	v_mul_f32_e32 v14, 0x45800000, v16
	v_cndmask_b32_e32 v14, v16, v14, vcc
	v_mul_f32_e32 v14, 0x3f4ccccd, v14
	v_pk_mul_f32 v[16:17], v[40:41], v[14:15] op_sel_hi:[1,0]
	v_pk_mul_f32 v[18:19], v[36:37], v[14:15] op_sel_hi:[1,0]
	s_waitcnt vmcnt(7)
	v_pk_mul_f32 v[10:11], v[10:11], v[16:17]
	v_pk_mul_f32 v[8:9], v[8:9], v[18:19]
	v_cvt_pk_bf16_f32 v11, v10, v11
	v_cvt_pk_bf16_f32 v10, v8, v9
	global_store_dwordx2 v[0:1], v[10:11], off
	v_pk_mul_f32 v[16:17], v[48:49], v[14:15] op_sel_hi:[1,0]
	v_pk_mul_f32 v[18:19], v[52:53], v[14:15] op_sel_hi:[1,0]
	v_pk_mul_f32 v[12:13], v[12:13], v[14:15] op_sel_hi:[1,0]
	v_pk_mul_f32 v[4:5], v[4:5], v[14:15] op_sel_hi:[1,0]
	v_pk_mul_f32 v[6:7], v[6:7], v[14:15] op_sel_hi:[1,0]
	v_readlane_b32 s91, v255, 33
	v_readlane_b32 s92, v255, 34
	v_readlane_b32 s93, v255, 35
	v_readlane_b32 s94, v255, 36
	v_readlane_b32 s95, v255, 37
	s_waitcnt vmcnt(7)
	v_pk_mul_f32 v[10:11], v[162:163], v[18:19]
	v_pk_mul_f32 v[8:9], v[160:161], v[16:17]
	v_pk_mul_f32 v[16:17], v[56:57], v[14:15] op_sel_hi:[1,0]
	v_cvt_pk_bf16_f32 v8, v8, v9
	v_cvt_pk_bf16_f32 v9, v10, v11
	global_store_dwordx2 v[0:1], v[8:9], off offset:32
	v_pk_mul_f32 v[18:19], v[58:59], v[14:15] op_sel_hi:[1,0]
	s_waitcnt vmcnt(7)
	v_pk_mul_f32 v[8:9], v[164:165], v[16:17]
	v_pk_mul_f32 v[10:11], v[166:167], v[18:19]
	v_cvt_pk_bf16_f32 v8, v8, v9
	v_cvt_pk_bf16_f32 v9, v10, v11
	global_store_dwordx2 v[0:1], v[8:9], off offset:64
	v_pk_mul_f32 v[16:17], v[24:25], v[14:15] op_sel_hi:[1,0]
	v_pk_mul_f32 v[18:19], v[26:27], v[14:15] op_sel_hi:[1,0]
	s_waitcnt vmcnt(7)
	v_pk_mul_f32 v[8:9], v[168:169], v[16:17]
	v_pk_mul_f32 v[10:11], v[170:171], v[18:19]
	v_cvt_pk_bf16_f32 v8, v8, v9
	v_cvt_pk_bf16_f32 v9, v10, v11
	global_store_dwordx2 v[0:1], v[8:9], off offset:96
	v_pk_mul_f32 v[16:17], v[60:61], v[14:15] op_sel_hi:[1,0]
	v_pk_mul_f32 v[18:19], v[62:63], v[14:15] op_sel_hi:[1,0]
	s_waitcnt vmcnt(7)
	v_pk_mul_f32 v[8:9], v[172:173], v[16:17]
	v_pk_mul_f32 v[10:11], v[174:175], v[18:19]
	v_cvt_pk_bf16_f32 v8, v8, v9
	v_cvt_pk_bf16_f32 v9, v10, v11
	global_store_dwordx2 v[0:1], v[8:9], off offset:128
	v_pk_mul_f32 v[16:17], v[28:29], v[14:15] op_sel_hi:[1,0]
	v_pk_mul_f32 v[18:19], v[30:31], v[14:15] op_sel_hi:[1,0]
	s_waitcnt vmcnt(7)
	v_pk_mul_f32 v[8:9], v[176:177], v[16:17]
	v_pk_mul_f32 v[10:11], v[178:179], v[18:19]
	v_cvt_pk_bf16_f32 v8, v8, v9
	v_cvt_pk_bf16_f32 v9, v10, v11
	global_store_dwordx2 v[0:1], v[8:9], off offset:160
	v_pk_mul_f32 v[16:17], v[20:21], v[14:15] op_sel_hi:[1,0]
	s_waitcnt vmcnt(7)
	v_pk_mul_f32 v[10:11], v[182:183], v[12:13]
	v_pk_mul_f32 v[8:9], v[180:181], v[16:17]
	s_nop 0
	v_cvt_pk_bf16_f32 v8, v8, v9
	v_cvt_pk_bf16_f32 v9, v10, v11
	global_store_dwordx2 v[0:1], v[8:9], off offset:192
	s_waitcnt vmcnt(7)
	v_pk_mul_f32 v[6:7], v[186:187], v[6:7]
	v_pk_mul_f32 v[4:5], v[184:185], v[4:5]
	s_nop 0
	v_cvt_pk_bf16_f32 v4, v4, v5
	v_cvt_pk_bf16_f32 v5, v6, v7
	global_store_dwordx2 v[0:1], v[4:5], off offset:224
